# MLA role split with an extra barrier between the matrix and vector phases (strict alternation of the two wave halves); hot loops page-contained
# speedup vs baseline: 1.0067x; 1.0009x over previous
; template <int GRP> __device__ __forceinline__ void att_stk(const AttCtx<GRP>& C, int buf, const u32x4& kreg, const u32x4& preg) {
;     *(LAS u32x4*)(C.lds + buf * KBUF + C.kwo) = kreg; if (GRP == 0 && C.tid < 256) *(LAS u32x4*)(C.lds + buf * KBUF + C.pwo) = preg;
; }
; template <int GRP> __device__ __forceinline__ void att_stld(const AttCtx<GRP>& C, int s, u32x4& kreg, u32x4& preg, u32x4& vreg) {
;     constexpr int NSTEP = 256;
;     if (s + 2 < NSTEP) att_stk<GRP>(C, s & 1, kreg, preg);
;     if (s + 1 < NSTEP) att_stv<GRP>(C, (s + 1) & 1, vreg);
;     if (s + 3 < NSTEP) att_ldk<GRP>(C, s + 3, kreg, preg);
;     if (s + 2 < NSTEP) att_ldv<GRP>(C, s + 2, vreg);
; }
; template <int GRP, bool has_next> __device__ __forceinline__ void att_step(const AttCtx<GRP>& C, AttState<GRP>& S, int s, f32x16& P0, f32x16& P1, f32x16& PN0, f32x16& PN1, u32x4& kreg, u32x4& preg, u32x4& vreg) {
;     ...
;     constexpr int NE = NKS - 1;
;     float ra = 0.f, rb = 0.f, rc = 0.f, rd = 0.f;
;     ...
; #pragma unroll
;     for (int c = 1; c < NKS; ++c) {
;         if (has_next) {
;             if (c == NK0) att_kfrag<GRP, NK0, NK1>(C, (s + 1) & 1, kfb);
;             const bf16x8 a0 = c < NK0 ? kfa[2 * c] : kfb[2 * (c - NK0)], a1 = c < NK0 ? kfa[2 * c + 1] : kfb[2 * (c - NK0) + 1];
;             PN0 = __builtin_amdgcn_mfma_f32_32x32x16_bf16(a0, S.qr[c], PN0, 0, 0, 0); PN1 = __builtin_amdgcn_mfma_f32_32x32x16_bf16(a1, S.qr[c], PN1, 0, 0, 0);
;         }
; #pragma unroll
;         for (int j = (c - 1) * 16 / NE; j < c * 16 / NE; ++j) {
;             if (j < 8) { P0[2 * j] = __builtin_amdgcn_exp2f(P0[2 * j]); P0[2 * j + 1] = __builtin_amdgcn_exp2f(P0[2 * j + 1]); }
;             else { P1[2 * (j - 8)] = __builtin_amdgcn_exp2f(P1[2 * (j - 8)]); P1[2 * (j - 8) + 1] = __builtin_amdgcn_exp2f(P1[2 * (j - 8) + 1]); }
;         }
;         if (c > 1) {
; #pragma unroll
;             for (int j = (c - 2) * 16 / NE; j < (c - 1) * 16 / NE; ++j) ATT_SUMPACK(j);
;         }
;         __builtin_amdgcn_sched_barrier(0);
;     }
;     if (has_next && S.refnz && t != 63) { PN0 = __builtin_amdgcn_mfma_f32_32x32x16_bf16(ones, qx, PN0, 0, 0, 0); PN1 = __builtin_amdgcn_mfma_f32_32x32x16_bf16(ones, qx, PN1, 0, 0, 0); }
;     att_vfrag<GRP>(C, s & 1, vf);
; #pragma unroll
;     for (int j = (NE - 1) * 16 / NE; j < 16; ++j) ATT_SUMPACK(j);
;     ...
;     S.lrun += (ra + rb) + (rc + rd);
.Lmla_nrz3:
	s_waitcnt lgkmcnt(3)
	v_mfma_f32_32x32x16_bf16 v[0:15], v[232:235], v[216:219], v[0:15]
	ds_read_b128 v[232:235], v157 offset:26688
	s_waitcnt lgkmcnt(3)
	v_mfma_f32_32x32x16_bf16 v[16:31], v[236:239], v[216:219], v[16:31]
	ds_read_b128 v[236:239], v157 offset:31296
	s_waitcnt lgkmcnt(3)
	v_mfma_f32_32x32x16_bf16 v[0:15], v[240:243], v[220:223], v[0:15]
	ds_read_b128 v[240:243], v157 offset:26720
	s_waitcnt lgkmcnt(3)
	v_mfma_f32_32x32x16_bf16 v[16:31], v[244:247], v[220:223], v[16:31]
	ds_read_b128 v[244:247], v157 offset:31328
	s_waitcnt lgkmcnt(3)
	v_mfma_f32_32x32x16_bf16 v[0:15], v[232:235], v[224:227], v[0:15]
	s_waitcnt lgkmcnt(2)
	v_mfma_f32_32x32x16_bf16 v[16:31], v[236:239], v[224:227], v[16:31]
	s_waitcnt lgkmcnt(1)
	v_mfma_f32_32x32x16_bf16 v[0:15], v[240:243], v[228:231], v[0:15]
	s_waitcnt lgkmcnt(0)
	v_mfma_f32_32x32x16_bf16 v[16:31], v[244:247], v[228:231], v[16:31]
	s_waitcnt lgkmcnt(0)
	s_barrier
	s_waitcnt vmcnt(1)
	ds_write_b128 v171, v[104:107]
	ds_write_b128 v172, v[100:103] offset:128
	s_mov_b32 s84, 0xfe000000
	s_mov_b32 s85, -1
	s_waitcnt vmcnt(0)
	ds_write_b128 v169, v[132:135] offset:35840
	v_lshl_add_u64 v[192:193], v[166:167], 0, s[84:85]
	s_add_i32 s14, s67, 0xfffff800
	s_and_b32 s14, s14, 0x1f800
	s_lshl_b32 s62, s14, 1
	global_load_dwordx4 v[104:107], v[192:193], off
	v_lshl_add_u64 v[190:191], v[160:161], 0, s[62:63]
	global_load_dwordx4 v[100:103], v[190:191], off
	s_mov_b32 s84, 0xffffe000
	s_nop 0
	v_lshl_add_u64 v[192:193], v[166:167], 0, s[84:85]
	global_load_dwordx4 v[132:135], v[192:193], off
	v_exp_f32_e32 v80, v80
	v_exp_f32_e32 v81, v81
	v_exp_f32_e32 v82, v82
	v_exp_f32_e32 v83, v83
	v_cvt_pk_bf16_f32 v216, v80, v81
	v_exp_f32_e32 v84, v84
	v_exp_f32_e32 v85, v85
	v_cvt_pk_bf16_f32 v217, v82, v83
	v_exp_f32_e32 v86, v86
	v_exp_f32_e32 v87, v87
	v_add_f32_e32 v248, v80, v84
	v_add_f32_e32 v249, v81, v85
	v_cvt_pk_bf16_f32 v218, v84, v85
	v_exp_f32_e32 v88, v88
	v_exp_f32_e32 v89, v89
	v_add_f32_e32 v250, v82, v86
	v_add_f32_e32 v251, v83, v87
	v_cvt_pk_bf16_f32 v219, v86, v87
	v_exp_f32_e32 v90, v90
	v_exp_f32_e32 v91, v91
	v_add_f32_e32 v248, v248, v88
	v_add_f32_e32 v249, v249, v89
	v_cvt_pk_bf16_f32 v220, v88, v89
	v_exp_f32_e32 v92, v92
	v_exp_f32_e32 v93, v93
	v_add_f32_e32 v250, v250, v90
	v_add_f32_e32 v251, v251, v91
	v_cvt_pk_bf16_f32 v221, v90, v91
	v_exp_f32_e32 v94, v94
	v_exp_f32_e32 v95, v95
	v_add_f32_e32 v248, v248, v92
	v_add_f32_e32 v249, v249, v93
	v_cvt_pk_bf16_f32 v222, v92, v93
	v_exp_f32_e32 v64, v64
	v_exp_f32_e32 v65, v65
	v_add_f32_e32 v250, v250, v94
	v_add_f32_e32 v251, v251, v95
	v_cvt_pk_bf16_f32 v223, v94, v95
	v_exp_f32_e32 v66, v66
	v_exp_f32_e32 v67, v67
	v_add_f32_e32 v248, v248, v64
	v_add_f32_e32 v249, v249, v65
	v_cvt_pk_bf16_f32 v224, v64, v65
	v_exp_f32_e32 v68, v68
	v_exp_f32_e32 v69, v69
	v_add_f32_e32 v250, v250, v66
	v_add_f32_e32 v251, v251, v67
	v_cvt_pk_bf16_f32 v225, v66, v67
	v_exp_f32_e32 v70, v70
	v_exp_f32_e32 v71, v71
	v_add_f32_e32 v248, v248, v68
	v_add_f32_e32 v249, v249, v69
	v_cvt_pk_bf16_f32 v226, v68, v69
	v_exp_f32_e32 v72, v72
	v_exp_f32_e32 v73, v73
	v_add_f32_e32 v250, v250, v70
	v_add_f32_e32 v251, v251, v71
	v_cvt_pk_bf16_f32 v227, v70, v71
	v_exp_f32_e32 v74, v74
	v_exp_f32_e32 v75, v75
	v_add_f32_e32 v248, v248, v72
	v_add_f32_e32 v249, v249, v73
	v_cvt_pk_bf16_f32 v228, v72, v73
	v_exp_f32_e32 v76, v76
	v_exp_f32_e32 v77, v77
	v_add_f32_e32 v250, v250, v74
	v_add_f32_e32 v251, v251, v75
	v_cvt_pk_bf16_f32 v229, v74, v75
	v_exp_f32_e32 v78, v78
	v_exp_f32_e32 v79, v79
	v_add_f32_e32 v248, v248, v76
	v_add_f32_e32 v249, v249, v77
	v_cvt_pk_bf16_f32 v230, v76, v77
	v_add_f32_e32 v250, v250, v78
	v_add_f32_e32 v251, v251, v79
	v_cvt_pk_bf16_f32 v231, v78, v79
	v_add_f32_e32 v248, v248, v249
	v_add_f32_e32 v250, v250, v251
	v_add_f32_e32 v248, v248, v250
	v_add_f32_e32 v170, v170, v248
	s_waitcnt lgkmcnt(0)
	s_barrier
	s_add_i32 s62, s69, 1
	s_lshr_b32 s71, s69, 6
	s_add_i32 s71, s71, s60
	s_and_b32 s10, s62, 63
	s_cmp_eq_u32 s10, 63
	s_cselect_b64 s[86:87], -1, 0
	s_cmp_lg_u64 s[86:87], 0
	s_cbranch_scc0 .Lmla_noq5
	s_mul_i32 s18, s71, 0x60
	s_ashr_i32 s19, s18, 31
	v_lshl_add_u64 v[192:193], s[18:19], 1, v[164:165]
	global_load_dwordx4 v[128:131], v[192:193], off offset:192
	global_load_dwordx4 v[124:127], v[192:193], off offset:224
	global_load_dwordx4 v[120:123], v[192:193], off offset:256
	global_load_dwordx4 v[116:119], v[192:193], off offset:288
	global_load_dwordx4 v[112:115], v[192:193], off offset:320
	global_load_dwordx4 v[108:111], v[192:193], off offset:352
	s_waitcnt vmcnt(0)

; #define LAS __attribute__((address_space(3)))
; template <int GRP> __device__ __forceinline__ void att_stk(const AttCtx<GRP>& C, int buf, const u32x4& kreg, const u32x4& preg) {
;     *(LAS u32x4*)(C.lds + buf * KBUF + C.kwo) = kreg; if (GRP == 0 && C.tid < 256) *(LAS u32x4*)(C.lds + buf * KBUF + C.pwo) = preg;
; }
; template <int GRP> __device__ __forceinline__ void att_stld(const AttCtx<GRP>& C, int s, u32x4& kreg, u32x4& preg, u32x4& vreg) {
;     constexpr int NSTEP = 256;
;     if (s + 2 < NSTEP) att_stk<GRP>(C, s & 1, kreg, preg);
;     if (s + 1 < NSTEP) att_stv<GRP>(C, (s + 1) & 1, vreg);
;     if (s + 3 < NSTEP) att_ldk<GRP>(C, s + 3, kreg, preg);
;     if (s + 2 < NSTEP) att_ldv<GRP>(C, s + 2, vreg);
.Lmla_nofin7:
	s_waitcnt lgkmcnt(0)
	s_barrier
	s_waitcnt vmcnt(1)
	ds_write_b128 v171, v[104:107] offset:13312
	ds_write_b128 v172, v[100:103] offset:13440
	s_waitcnt vmcnt(0)
	ds_write_b128 v173, v[132:135] offset:26624
	s_cmpk_gt_u32 s62, 0xfc
	s_cbranch_scc1 .Lmla_nold8
	s_mov_b32 s88, s70
	s_ashr_i32 s89, s70, 31
	v_lshl_add_u64 v[192:193], s[88:89], 1, v[158:159]
	s_and_b32 s14, s67, 0x1f000
	s_lshl_b32 s14, s14, 1
	s_mov_b32 s15, 0
	global_load_dwordx4 v[104:107], v[192:193], off
	v_lshl_add_u64 v[190:191], v[160:161], 0, s[14:15]
	global_load_dwordx4 v[100:103], v[190:191], off

; template <int GRP> ...
;     ...
;     if (wid >= 4) __builtin_amdgcn_s_setprio(1);
;     asm volatile("s_nop 15\n\ts_nop 7" : "+v"(pa0), "+v"(pa1));
;     for (int s = 0; s < NSTEP - 2; s += 2) { att_step<GRP, true>(C, S, s, pa0, pa1, pb0, pb1, kA, pA, vA); att_step<GRP, true>(C, S, s + 1, pb0, pb1, pa0, pa1, kA, pA, vA); }
.Lmla_T_entry:
	s_setprio 1
	s_branch .Lpagefit_3
	s_nop 0
	s_nop 0
	s_nop 0
	s_nop 0
	s_nop 0
	s_nop 0
	s_nop 0
	s_nop 0
	s_nop 0
	s_nop 0
	s_nop 0
	s_nop 0
	s_nop 0
	s_nop 0
	s_nop 0
	s_nop 0
	s_nop 0
	s_nop 0
	s_nop 0
	s_nop 0
	s_nop 0
	s_nop 0
	s_nop 0
	s_nop 0
	s_nop 0
	s_nop 0
	s_nop 0
	s_nop 0
	s_nop 0
	s_nop 0
	s_nop 0
	s_nop 0
	s_nop 0
	s_nop 0
	s_nop 0
	s_nop 0
	s_nop 0
	s_nop 0
	s_nop 0
	s_nop 0
	s_nop 0
	s_nop 0
	s_nop 0
	s_nop 0
	s_nop 0
	s_nop 0
	s_nop 0
	s_nop 0
	s_nop 0
	s_nop 0
	s_nop 0
	s_nop 0
	s_nop 0
	s_nop 0
	s_nop 0
	s_nop 0
	s_nop 0
	s_nop 0
	s_nop 0
	s_nop 0
	s_nop 0
	s_nop 0
	s_nop 0
	s_nop 0
	s_nop 0
	s_nop 0
	s_nop 0
	s_nop 0
	s_nop 0
	s_nop 0
	s_nop 0
	s_nop 0
	s_nop 0
	s_nop 0
	s_nop 0
	s_nop 0
	s_nop 0
	s_nop 0
	s_nop 0
	s_nop 0
	s_nop 0
	s_nop 0
	s_nop 0
	s_nop 0
	s_nop 0
	s_nop 0
	s_nop 0
	s_nop 0
	s_nop 0
	s_nop 0
	s_nop 0
	s_nop 0
	s_nop 0
	s_nop 0
	s_nop 0
	s_nop 0
	s_nop 0
	s_nop 0
	s_nop 0
	s_nop 0
	s_nop 0
	s_nop 0
	s_nop 0
	s_nop 0
	s_nop 0
	s_nop 0
	s_nop 0
	s_nop 0
	s_nop 0
	s_nop 0
	s_nop 0
	s_nop 0
	s_nop 0
	s_nop 0
	s_nop 0
	s_nop 0
	s_nop 0
	s_nop 0
	s_nop 0
	s_nop 0
	s_nop 0
	s_nop 0
	s_nop 0
	s_nop 0
	s_nop 0
	s_nop 0
	s_nop 0
	s_nop 0
	s_nop 0
	s_nop 0
	s_nop 0
	s_nop 0
	s_nop 0
	s_nop 0
	s_nop 0
	s_nop 0
	s_nop 0
	s_nop 0
	s_nop 0
	s_nop 0
	s_nop 0
	s_nop 0
	s_nop 0
	s_nop 0
	s_nop 0
	s_nop 0
	s_nop 0
	s_nop 0
	s_nop 0
	s_nop 0
	s_nop 0
	s_nop 0
	s_nop 0
	s_nop 0
	s_nop 0
	s_nop 0
	s_nop 0
	s_nop 0
	s_nop 0
	s_nop 0
	s_nop 0
	s_nop 0
	s_nop 0
	s_nop 0
	s_nop 0
	s_nop 0
	s_nop 0
	s_nop 0
	s_nop 0
	s_nop 0
	s_nop 0
	s_nop 0
	s_nop 0
	s_nop 0
	s_nop 0
	s_nop 0
	s_nop 0
	s_nop 0
	s_nop 0
	s_nop 0
	s_nop 0
	s_nop 0
	s_nop 0
	s_nop 0
	s_nop 0
	s_nop 0
	s_nop 0
	s_nop 0
	s_nop 0
	s_nop 0
	s_nop 0
	s_nop 0
	s_nop 0
	s_nop 0
	s_nop 0
	s_nop 0
	s_nop 0
	s_nop 0
	s_nop 0
	s_nop 0
	s_nop 0
	s_nop 0
	s_nop 0
	s_nop 0
	s_nop 0
	s_nop 0
	s_nop 0
	s_nop 0
	s_nop 0
	s_nop 0
	s_nop 0
	s_nop 0
	s_nop 0
	s_nop 0
	s_nop 0
	s_nop 0
	s_nop 0
	s_nop 0
	s_nop 0
	s_nop 0
	s_nop 0
	s_nop 0
	s_nop 0
	s_nop 0
	s_nop 0
	s_nop 0
	s_nop 0
	s_nop 0
	s_nop 0
	s_nop 0
	s_nop 0
	s_nop 0
	s_nop 0
	s_nop 0
	s_nop 0
	s_nop 0
	s_nop 0
	s_nop 0
	s_nop 0
	s_nop 0
	s_nop 0
	s_nop 0
	s_nop 0
	s_nop 0
	s_nop 0
	s_nop 0
	s_nop 0
	s_nop 0
	s_nop 0
	s_nop 0
	s_nop 0
	s_nop 0
	s_nop 0
	s_nop 0
	s_nop 0
	s_nop 0
	s_nop 0
	s_nop 0
	s_nop 0
	s_nop 0
	s_nop 0
	s_nop 0
	s_nop 0
	s_nop 0
	s_nop 0
	s_nop 0
	s_nop 0
	s_nop 0
	s_nop 0
	s_nop 0
	s_nop 0
	s_nop 0
	s_nop 0
	s_nop 0
	s_nop 0
	s_nop 0
	s_nop 0
	s_nop 0
	s_nop 0
	s_nop 0
	s_nop 0
	s_nop 0
	s_nop 0
	s_nop 0
	s_nop 0
	s_nop 0
	s_nop 0
	s_nop 0
	s_nop 0
	s_nop 0
	s_nop 0
	s_nop 0
	s_nop 0
	s_nop 0
	s_nop 0
	s_nop 0
	s_nop 0
	s_nop 0
	s_nop 0
	s_nop 0
	s_nop 0
	s_nop 0
	s_nop 0
	s_nop 0
	s_nop 0
	s_nop 0
	s_nop 0
	s_nop 0
	s_nop 0
	s_nop 0
	s_nop 0
	s_nop 0
	s_nop 0
	s_nop 0
	s_nop 0
	s_nop 0
	s_nop 0
	s_nop 0
	s_nop 0
	s_nop 0
	s_nop 0
	s_nop 0
	s_nop 0
	s_nop 0
	s_nop 0
	s_nop 0
	s_nop 0
	s_nop 0
	s_nop 0
	s_nop 0
	s_nop 0
	s_nop 0
	s_nop 0
	s_nop 0
	s_nop 0
	s_nop 0
	s_nop 0
	s_nop 0
	s_nop 0
	s_nop 0
	s_nop 0
	s_nop 0
	s_nop 0
	s_nop 0
	s_nop 0
	s_nop 0
	s_nop 0
	s_nop 0
	s_nop 0
	s_nop 0
	s_nop 0
	s_nop 0
	s_nop 0
	s_nop 0
	s_nop 0
	s_nop 0
	s_nop 0
	s_nop 0
	s_nop 0
	s_nop 0
	s_nop 0
	s_nop 0
	s_nop 0
	s_nop 0
	s_nop 0
	s_nop 0
	s_nop 0
	s_nop 0
	s_nop 0
	s_nop 0
	s_nop 0
	s_nop 0
	s_nop 0
	s_nop 0
	s_nop 0
	s_nop 0
	s_nop 0
	s_nop 0
	s_nop 0
	s_nop 0
	s_nop 0
	s_nop 0
	s_nop 0
	s_nop 0
	s_nop 0
	s_nop 0
	s_nop 0
	s_nop 0
	s_nop 0
	s_nop 0
	s_nop 0
	s_nop 0
	s_nop 0
	s_nop 0
	s_nop 0
	s_nop 0
	s_nop 0
	s_nop 0
	s_nop 0
	s_nop 0
	s_nop 0
	s_nop 0
	s_nop 0
	s_nop 0
	s_nop 0
	s_nop 0
	s_nop 0
	s_nop 0
	s_nop 0
	s_nop 0
	s_nop 0
	s_nop 0
	s_nop 0
	s_nop 0
	s_nop 0
	s_nop 0
	s_nop 0
	s_nop 0
	s_nop 0
	s_nop 0
	s_nop 0
	s_nop 0
	s_nop 0
	s_nop 0
	s_nop 0
	s_nop 0
	s_nop 0
	s_nop 0
	s_nop 0
	s_nop 0
	s_nop 0
	s_nop 0
	s_nop 0
	s_nop 0
	s_nop 0
	s_nop 0
	s_nop 0
	s_nop 0
	s_nop 0
	s_nop 0
	s_nop 0
	s_nop 0
	s_nop 0
	s_nop 0
	s_nop 0
	s_nop 0
	s_nop 0
	s_nop 0
	s_nop 0
	s_nop 0
	s_nop 0
	s_nop 0
	s_nop 0
	s_nop 0
	s_nop 0
	s_nop 0
	s_nop 0
	s_nop 0
	s_nop 0
	s_nop 0
	s_nop 0
	s_nop 0
	s_nop 0
	s_nop 0
	s_nop 0
	s_nop 0
	s_nop 0
	s_nop 0
	s_nop 0
	s_nop 0
	s_nop 0
	s_nop 0
	s_nop 0
	s_nop 0
	s_nop 0
	s_nop 0
	s_nop 0
	s_nop 0
	s_nop 0
	s_nop 0
	s_nop 0
	s_nop 0
	s_nop 0
	s_nop 0
	s_nop 0
	s_nop 0
	s_nop 0
	s_nop 0
	s_nop 0
	s_nop 0
	s_nop 0
	s_nop 0
	s_nop 0
	s_nop 0
	s_nop 0
	s_nop 0
	s_nop 0
	s_nop 0
	s_nop 0
	s_nop 0
	s_nop 0
	s_nop 0
	s_nop 0
	s_nop 0
	s_nop 0
	s_nop 0
	s_nop 0
	s_nop 0
	s_nop 0
	s_nop 0
	s_nop 0
	s_nop 0
	s_nop 0
	s_nop 0
	s_nop 0
	s_nop 0
	s_nop 0
	s_nop 0
	s_nop 0
	s_nop 0
	s_nop 0
	s_nop 0
	s_nop 0
	s_nop 0
	s_nop 0
	s_nop 0
	s_nop 0
	s_nop 0
	s_nop 0
	s_nop 0
	s_nop 0
	s_nop 0
	s_nop 0
	s_nop 0
	s_nop 0
	s_nop 0
	s_nop 0
	s_nop 0
	s_nop 0
	s_nop 0
	s_nop 0
	s_nop 0
	s_nop 0
	s_nop 0
	s_nop 0
	s_nop 0
	s_nop 0
	s_nop 0
	s_nop 0
	s_nop 0
	s_nop 0
	s_nop 0
	s_nop 0
	s_nop 0
	s_nop 0
	s_nop 0
	s_nop 0
	s_nop 0
	s_nop 0
	s_nop 0
	s_nop 0
	s_nop 0
	s_nop 0
	s_nop 0
	s_nop 0
	s_nop 0
	s_nop 0
	s_nop 0
	s_nop 0
	s_nop 0
	s_nop 0
	s_nop 0
	s_nop 0
	s_nop 0
	s_nop 0
	s_nop 0
	s_nop 0
	s_nop 0
	s_nop 0
	s_nop 0
	s_nop 0
	s_nop 0
	s_nop 0
	s_nop 0
	s_nop 0
	s_nop 0
	s_nop 0
	s_nop 0
	s_nop 0
	s_nop 0
	s_nop 0
	s_nop 0
	s_nop 0
	s_nop 0
	s_nop 0
	s_nop 0
	s_nop 0
	s_nop 0
	s_nop 0
	s_nop 0
	s_nop 0
	s_nop 0
	s_nop 0
	s_nop 0
	s_nop 0
	s_nop 0
	s_nop 0
	s_nop 0
	s_nop 0
	s_nop 0
	s_nop 0
	s_nop 0
	s_nop 0
	s_nop 0
	s_nop 0
	s_nop 0
	s_nop 0
	s_nop 0
	s_nop 0
	s_nop 0
	s_nop 0
	s_nop 0
	s_nop 0
	s_nop 0
	s_nop 0
	s_nop 0
	s_nop 0
	s_nop 0
	s_nop 0
	s_nop 0
	s_nop 0
	s_nop 0
	s_nop 0
	s_nop 0
	s_nop 0
	s_nop 0
	s_nop 0
	s_nop 0
	s_nop 0
	s_nop 0
	s_nop 0
	s_nop 0
	s_nop 0
	s_nop 0
	s_nop 0
	s_nop 0
; #define LAS __attribute__((address_space(3)))
; __device__ __forceinline__ float xhalf_max(float m) { auto rr = __builtin_amdgcn_permlane32_swap(__float_as_uint(m), __float_as_uint(m), false, false); return fmaxf(__uint_as_float(rr[0]), __uint_as_float(rr[1])); }
; __device__ __forceinline__ float max3f(float a, float b, float c) { float r; asm("v_max3_f32 %0, %1, %2, %3" : "=v"(r) : "v"(a), "v"(b), "v"(c)); return r; }
; __device__ __forceinline__ float max2f(float a, float b) { float r; asm("v_max_f32_e32 %0, %1, %2" : "=v"(r) : "v"(a), "v"(b)); return r; }
; template <int GRP> __device__ __forceinline__ void att_stk(const AttCtx<GRP>& C, int buf, const u32x4& kreg, const u32x4& preg) {
;     *(LAS u32x4*)(C.lds + buf * KBUF + C.kwo) = kreg; if (GRP == 0 && C.tid < 256) *(LAS u32x4*)(C.lds + buf * KBUF + C.pwo) = preg;
; }
; template <int GRP> __device__ __forceinline__ void att_stld(const AttCtx<GRP>& C, int s, u32x4& kreg, u32x4& preg, u32x4& vreg) {
;     constexpr int NSTEP = 256;
;     if (s + 2 < NSTEP) att_stk<GRP>(C, s & 1, kreg, preg);
;     if (s + 1 < NSTEP) att_stv<GRP>(C, (s + 1) & 1, vreg);
;     if (s + 3 < NSTEP) att_ldk<GRP>(C, s + 3, kreg, preg);
;     if (s + 2 < NSTEP) att_ldv<GRP>(C, s + 2, vreg);
; template <int GRP, bool has_next> __device__ __forceinline__ void att_step(const AttCtx<GRP>& C, AttState<GRP>& S, int s, f32x16& P0, f32x16& P1, f32x16& PN0, f32x16& PN1, u32x4& kreg, u32x4& preg, u32x4& vreg) {
;     ...
;     if ((t & 7) == 0) {
;         float ma = max3f(P0[0], P0[1], P0[2]), mb = max3f(P0[3], P0[4], P0[5]), mc = max3f(P1[0], P1[1], P1[2]), md = max3f(P1[3], P1[4], P1[5]);
;         ma = max3f(ma, P0[6], P0[7]); mb = max3f(mb, P0[8], P0[9]); mc = max3f(mc, P1[6], P1[7]); md = max3f(md, P1[8], P1[9]);
;         ma = max3f(ma, P0[10], P0[11]); mb = max3f(mb, P0[12], P0[13]); mc = max3f(mc, P1[10], P1[11]); md = max3f(md, P1[12], P1[13]);
;         ma = max3f(ma, P0[14], P0[15]); mc = max3f(mc, P1[14], P1[15]); ma = max3f(ma, mb, mc); mb = md;
;         const float mx = xhalf_max(max2f(ma, mb));
;         const int up = __any(mx > THR), dn = (t == 0) ? __any(mx < -THR) : 0;
.Lpagefit_3:
.LBB0_776:
	s_waitcnt vmcnt(1)
	ds_write_b128 v171, v[104:107]
	s_mov_b32 s84, 0xfe000000
	s_mov_b32 s85, -1
	s_waitcnt vmcnt(0)
	ds_write_b128 v169, v[132:135] offset:35840
	v_lshl_add_u64 v[192:193], v[166:167], 0, s[84:85]
	global_load_dwordx4 v[104:107], v[192:193], off
	s_mov_b32 s84, 0xffffe000
	s_nop 0
	v_lshl_add_u64 v[192:193], v[166:167], 0, s[84:85]
	global_load_dwordx4 v[132:135], v[192:193], off
	s_and_b32 s10, s69, 6
	s_cmp_lg_u32 s10, 0
	s_cbranch_scc1 .Lmla_nomax13
	v_max3_f32 v96, v48, v49, v50
	v_max3_f32 v99, v32, v33, v34
	v_max3_f32 v98, v51, v52, v53
	v_max3_f32 v252, v35, v36, v37
	s_and_b32 s14, s69, 56
	v_max3_f32 v96, v96, v54, v55
	v_max3_f32 v99, v99, v38, v39
	v_max3_f32 v98, v98, v56, v57
	v_max3_f32 v252, v252, v40, v41
	s_cmp_eq_u32 s14, 0
	v_max3_f32 v96, v96, v58, v59
	v_max3_f32 v99, v99, v42, v43
	v_max3_f32 v98, v98, v60, v61
	v_max3_f32 v252, v252, v44, v45
	s_cselect_b64 s[10:11], -1, 0
	v_max3_f32 v96, v96, v62, v63
	v_max3_f32 v99, v99, v46, v47
	s_cmp_lg_u32 s14, 0
	v_max3_f32 v96, v96, v98, v99
	s_nop 0
	v_max_f32_e32 v96, v96, v252
	s_nop 0
	v_mov_b32_e32 v98, v96
	s_nop 1
	v_permlane32_swap_b32_e32 v96, v98
	v_max_f32_e32 v98, v98, v98
	v_max_f32_e32 v96, v96, v96
	v_max_f32_e32 v96, v96, v98
	v_cmp_lt_f32_e32 vcc, s54, v96
	v_mov_b32_e32 v98, 0
	s_cbranch_scc1 .Lmla_mx14
	v_cmp_gt_f32_e64 s[14:15], s55, v96
	s_cmp_lg_u64 s[14:15], 0
	s_cselect_b64 s[14:15], -1, 0
	v_cndmask_b32_e64 v98, 0, 1, s[14:15]

; __device__ __forceinline__ float max2f(float a, float b) { float r; asm("v_max_f32_e32 %0, %1, %2" : "=v"(r) : "v"(a), "v"(b)); return r; }
; template <int GRP, bool has_next> __device__ __forceinline__ void att_step(const AttCtx<GRP>& C, AttState<GRP>& S, int s, f32x16& P0, f32x16& P1, f32x16& PN0, f32x16& PN1, u32x4& kreg, u32x4& preg, u32x4& vreg) {
;     ...
;         att_kfrag<GRP, 0, NK0>(C, (s + 1) & 1, kfa);
;     }
;     if (has_next) { PN0 = __builtin_amdgcn_mfma_f32_32x32x16_bf16(kfa[0], S.qr[0], (f32x16){}, 0, 0, 0); PN1 = __builtin_amdgcn_mfma_f32_32x32x16_bf16(kfa[1], S.qr[0], (f32x16){}, 0, 0, 0); }
;     if ((t & 7) == 0) {
;         float ma = max3f(P0[0], P0[1], P0[2]), mb = max3f(P0[3], P0[4], P0[5]), mc = max3f(P1[0], P1[1], P1[2]), md = max3f(P1[3], P1[4], P1[5]);
;         ma = max3f(ma, P0[6], P0[7]); mb = max3f(mb, P0[8], P0[9]); mc = max3f(mc, P1[6], P1[7]); md = max3f(md, P1[8], P1[9]);
;         ma = max3f(ma, P0[10], P0[11]); mb = max3f(mb, P0[12], P0[13]); mc = max3f(mc, P1[10], P1[11]); md = max3f(md, P1[12], P1[13]);
;         ma = max3f(ma, P0[14], P0[15]); mc = max3f(mc, P1[14], P1[15]); ma = max3f(ma, mb, mc); mb = md;
;         const float mx = xhalf_max(max2f(ma, mb));
;         const int up = __any(mx > THR), dn = (t == 0) ? __any(mx < -THR) : 0;
;         if (up | dn) {
;             const float dl = ceilf((t == 0) ? mx : fmaxf(mx, 0.f));
;             const float f = (t == 0) ? 0.f : __builtin_amdgcn_exp2f(-dl);
;             S.mhat += dl; S.lrun *= f;
; #pragma unroll
;             for (int r = 0; r < 16; ++r) { P0[r] -= dl; P1[r] -= dl; S.o0[r] *= f; S.o1[r] *= f; }
;             S.refnz = __any(S.mhat != 0.f);
;         }
;     }
;     __builtin_amdgcn_sched_barrier(0);
;     const unsigned mbits = (t == 63 || C.hi != 0) ? 0u : (__float_as_uint(-S.mhat) >> 16);
;     const u32x4 qxw = {mbits, 0u, 0u, 0u}; const bf16x8 qx = __builtin_bit_cast(bf16x8, qxw);
;     const bf16x8 ones = {0x3f80, 0x3f80, 0x3f80, 0x3f80, 0x3f80, 0x3f80, 0x3f80, 0x3f80};
;     constexpr int NE = NKS - 1;
;     float ra = 0.f, rb = 0.f, rc = 0.f, rd = 0.f;
;     ...
; #pragma unroll
;     for (int c = 1; c < NKS; ++c) {
;         if (has_next) {
;             if (c == NK0) att_kfrag<GRP, NK0, NK1>(C, (s + 1) & 1, kfb);
;             const bf16x8 a0 = c < NK0 ? kfa[2 * c] : kfb[2 * (c - NK0)], a1 = c < NK0 ? kfa[2 * c + 1] : kfb[2 * (c - NK0) + 1];
.Lmla_nomax13:
	v_exp_f32_e32 v48, v48
	v_exp_f32_e32 v49, v49
	v_exp_f32_e32 v50, v50
	v_exp_f32_e32 v51, v51
	v_cvt_pk_bf16_f32 v216, v48, v49
	v_exp_f32_e32 v52, v52
	v_exp_f32_e32 v53, v53
	v_cvt_pk_bf16_f32 v217, v50, v51
	v_exp_f32_e32 v54, v54
	v_exp_f32_e32 v55, v55
	v_add_f32_e32 v248, v48, v52
	v_add_f32_e32 v249, v49, v53
	v_cvt_pk_bf16_f32 v218, v52, v53
	v_exp_f32_e32 v56, v56
	v_exp_f32_e32 v57, v57
	v_add_f32_e32 v250, v50, v54
	v_add_f32_e32 v251, v51, v55
	v_cvt_pk_bf16_f32 v219, v54, v55
	v_exp_f32_e32 v58, v58
	v_exp_f32_e32 v59, v59
	v_add_f32_e32 v248, v248, v56
	v_add_f32_e32 v249, v249, v57
	v_cvt_pk_bf16_f32 v220, v56, v57
	v_exp_f32_e32 v60, v60
	v_exp_f32_e32 v61, v61
	v_add_f32_e32 v250, v250, v58
	v_add_f32_e32 v251, v251, v59
	v_cvt_pk_bf16_f32 v221, v58, v59
	v_exp_f32_e32 v62, v62
	v_exp_f32_e32 v63, v63
	v_add_f32_e32 v248, v248, v60
	v_add_f32_e32 v249, v249, v61
	v_cvt_pk_bf16_f32 v222, v60, v61
	v_exp_f32_e32 v32, v32
	v_exp_f32_e32 v33, v33
	v_add_f32_e32 v250, v250, v62
	v_add_f32_e32 v251, v251, v63
	v_cvt_pk_bf16_f32 v223, v62, v63
	v_exp_f32_e32 v34, v34
	v_exp_f32_e32 v35, v35
	v_add_f32_e32 v248, v248, v32
	v_add_f32_e32 v249, v249, v33
	v_cvt_pk_bf16_f32 v224, v32, v33
	v_exp_f32_e32 v36, v36
	v_exp_f32_e32 v37, v37
	v_add_f32_e32 v250, v250, v34
	v_add_f32_e32 v251, v251, v35
	v_cvt_pk_bf16_f32 v225, v34, v35
	v_exp_f32_e32 v38, v38
	v_exp_f32_e32 v39, v39
	v_add_f32_e32 v248, v248, v36
	v_add_f32_e32 v249, v249, v37
	v_cvt_pk_bf16_f32 v226, v36, v37
	v_exp_f32_e32 v40, v40
	v_exp_f32_e32 v41, v41
	v_add_f32_e32 v250, v250, v38
	v_add_f32_e32 v251, v251, v39
	v_cvt_pk_bf16_f32 v227, v38, v39
	v_exp_f32_e32 v42, v42
	v_exp_f32_e32 v43, v43
	v_add_f32_e32 v248, v248, v40
	v_add_f32_e32 v249, v249, v41
	v_cvt_pk_bf16_f32 v228, v40, v41
	v_exp_f32_e32 v44, v44
	v_exp_f32_e32 v45, v45
	v_add_f32_e32 v250, v250, v42
	v_add_f32_e32 v251, v251, v43
	v_cvt_pk_bf16_f32 v229, v42, v43
	v_exp_f32_e32 v46, v46
	v_exp_f32_e32 v47, v47
	v_add_f32_e32 v248, v248, v44
	v_add_f32_e32 v249, v249, v45
	v_cvt_pk_bf16_f32 v230, v44, v45
	v_add_f32_e32 v250, v250, v46
	v_add_f32_e32 v251, v251, v47
	v_cvt_pk_bf16_f32 v231, v46, v47
	v_add_f32_e32 v248, v248, v249
	v_add_f32_e32 v250, v250, v251
	v_add_f32_e32 v248, v248, v250
	v_add_f32_e32 v170, v170, v248
	s_waitcnt lgkmcnt(0)
	s_barrier
	ds_read_b128 v[136:139], v174 offset:13312
	ds_read_b128 v[140:143], v174 offset:19968
	ds_read_b128 v[144:147], v174 offset:13344
	ds_read_b128 v[148:151], v174 offset:20000
	ds_read_b128 v[176:179], v174 offset:13376
	ds_read_b128 v[180:183], v174 offset:20032
	s_waitcnt lgkmcnt(5)
	v_mfma_f32_32x32x16_bf16 v[80:95], v[136:139], v[128:131], 0
	ds_read_b128 v[136:139], v174 offset:13408
	s_waitcnt lgkmcnt(5)
	v_mfma_f32_32x32x16_bf16 v[64:79], v[140:143], v[128:131], 0
	ds_read_b128 v[140:143], v174 offset:20064
	s_waitcnt lgkmcnt(5)
	v_mfma_f32_32x32x16_bf16 v[80:95], v[144:147], v[124:127], v[80:95]
	ds_read_b128 v[144:147], v174 offset:13440
	s_waitcnt lgkmcnt(5)
	v_mfma_f32_32x32x16_bf16 v[64:79], v[148:151], v[124:127], v[64:79]
	ds_read_b128 v[148:151], v174 offset:20096
	s_waitcnt lgkmcnt(5)
	v_mfma_f32_32x32x16_bf16 v[80:95], v[176:179], v[120:123], v[80:95]
	ds_read_b128 v[176:179], v174 offset:13472
	s_waitcnt lgkmcnt(5)
	v_mfma_f32_32x32x16_bf16 v[64:79], v[180:183], v[120:123], v[64:79]
	ds_read_b128 v[180:183], v174 offset:20128
	s_waitcnt lgkmcnt(5)
	v_mfma_f32_32x32x16_bf16 v[80:95], v[136:139], v[116:119], v[80:95]
	ds_read_b128 v[232:235], v157 offset:26624
	s_waitcnt lgkmcnt(5)
	v_mfma_f32_32x32x16_bf16 v[64:79], v[140:143], v[116:119], v[64:79]
	ds_read_b128 v[236:239], v157 offset:31232
	s_waitcnt lgkmcnt(5)
	v_mfma_f32_32x32x16_bf16 v[80:95], v[144:147], v[112:115], v[80:95]
	ds_read_b128 v[240:243], v157 offset:26656
	s_waitcnt lgkmcnt(5)
	v_mfma_f32_32x32x16_bf16 v[64:79], v[148:151], v[112:115], v[64:79]
	ds_read_b128 v[244:247], v157 offset:31264
	s_waitcnt lgkmcnt(5)
	v_mfma_f32_32x32x16_bf16 v[80:95], v[176:179], v[108:111], v[80:95]
	s_waitcnt lgkmcnt(4)
	v_mfma_f32_32x32x16_bf16 v[64:79], v[180:183], v[108:111], v[64:79]
	s_cmp_eq_u32 s72, 0
	s_cbranch_scc1 .Lmla_nrz15
	v_xor_b32_e32 v195, 0x80000000, v175
	s_mov_b32 s18, s16
	s_mov_b32 s19, s16
	s_mov_b32 s17, s16
	v_mov_b64_e32 v[186:187], s[18:19]
	v_mov_b64_e32 v[184:185], s[16:17]
	s_mov_b64 vcc, s[0:1]
	v_cndmask_b32_sdwa v96, v97, v195, vcc dst_sel:DWORD dst_unused:UNUSED_PAD src0_sel:DWORD src1_sel:WORD_1
	v_mov_b32_e32 v98, v97
	v_mov_b32_e32 v99, v97
	s_nop 1
	v_mfma_f32_32x32x16_bf16 v[80:95], v[184:187], v[96:99], v[80:95]
	v_mfma_f32_32x32x16_bf16 v[64:79], v[184:187], v[96:99], v[64:79]

; #define ATT_SUMPACK(j) do { const float e0_ = (j) < 8 ? P0[2 * ((j) & 7)] : P1[2 * ((j) & 7)], e1_ = (j) < 8 ? P0[2 * ((j) & 7) + 1] : P1[2 * ((j) & 7) + 1]; \
;         if ((j) & 1) { rc += e0_; rd += e1_; } else { ra += e0_; rb += e1_; } S.pw[j] = cvtpk(e0_, e1_); } while (0)
; template <int GRP, bool has_next> __device__ __forceinline__ void att_step(const AttCtx<GRP>& C, AttState<GRP>& S, int s, f32x16& P0, f32x16& P1, f32x16& PN0, f32x16& PN1, u32x4& kreg, u32x4& preg, u32x4& vreg) {
;     ...
;         if (t == 63) {
; #pragma unroll
;             for (int ks = 0; ks < NKS; ++ks) S.qr[ks] = *(const bf16x8*)(C.Q + C.qrow * QP + (h + 1) * DK + ks * 16 + C.hi * 8);
;     ...
;     constexpr int NE = NKS - 1;
;     float ra = 0.f, rb = 0.f, rc = 0.f, rd = 0.f;
;     ...
; #pragma unroll
;     for (int c = 1; c < NKS; ++c) {
;         if (has_next) {
;             if (c == NK0) att_kfrag<GRP, NK0, NK1>(C, (s + 1) & 1, kfb);
;             const bf16x8 a0 = c < NK0 ? kfa[2 * c] : kfb[2 * (c - NK0)], a1 = c < NK0 ? kfa[2 * c + 1] : kfb[2 * (c - NK0) + 1];
;             PN0 = __builtin_amdgcn_mfma_f32_32x32x16_bf16(a0, S.qr[c], PN0, 0, 0, 0); PN1 = __builtin_amdgcn_mfma_f32_32x32x16_bf16(a1, S.qr[c], PN1, 0, 0, 0);
;         }
; #pragma unroll
;         for (int j = (c - 1) * 16 / NE; j < c * 16 / NE; ++j) {
;             if (j < 8) { P0[2 * j] = __builtin_amdgcn_exp2f(P0[2 * j]); P0[2 * j + 1] = __builtin_amdgcn_exp2f(P0[2 * j + 1]); }
;             else { P1[2 * (j - 8)] = __builtin_amdgcn_exp2f(P1[2 * (j - 8)]); P1[2 * (j - 8) + 1] = __builtin_amdgcn_exp2f(P1[2 * (j - 8) + 1]); }
;         }
;         if (c > 1) {
; #pragma unroll
;             for (int j = (c - 2) * 16 / NE; j < (c - 1) * 16 / NE; ++j) ATT_SUMPACK(j);
;         }
;         __builtin_amdgcn_sched_barrier(0);
;     }
;     if (has_next && S.refnz && t != 63) { PN0 = __builtin_amdgcn_mfma_f32_32x32x16_bf16(ones, qx, PN0, 0, 0, 0); PN1 = __builtin_amdgcn_mfma_f32_32x32x16_bf16(ones, qx, PN1, 0, 0, 0); }
;     att_vfrag<GRP>(C, s & 1, vf);
; #pragma unroll
;     for (int j = (NE - 1) * 16 / NE; j < 16; ++j) ATT_SUMPACK(j);
;     ...
;     S.lrun += (ra + rb) + (rc + rd);
.Lmla_nold17:
	global_load_dwordx4 v[132:135], v[166:167], off
	v_exp_f32_e32 v80, v80
	v_exp_f32_e32 v81, v81
	v_exp_f32_e32 v82, v82
	v_exp_f32_e32 v83, v83
	v_cvt_pk_bf16_f32 v216, v80, v81
	v_exp_f32_e32 v84, v84
	v_exp_f32_e32 v85, v85
	v_cvt_pk_bf16_f32 v217, v82, v83
	v_exp_f32_e32 v86, v86
	v_exp_f32_e32 v87, v87
	v_add_f32_e32 v248, v80, v84
	v_add_f32_e32 v249, v81, v85
	v_cvt_pk_bf16_f32 v218, v84, v85
	v_exp_f32_e32 v88, v88
	v_exp_f32_e32 v89, v89
	v_add_f32_e32 v250, v82, v86
	v_add_f32_e32 v251, v83, v87
	v_cvt_pk_bf16_f32 v219, v86, v87
	v_exp_f32_e32 v90, v90
	v_exp_f32_e32 v91, v91
	v_add_f32_e32 v248, v248, v88
	v_add_f32_e32 v249, v249, v89
	v_cvt_pk_bf16_f32 v220, v88, v89
	v_exp_f32_e32 v92, v92
	v_exp_f32_e32 v93, v93
	v_add_f32_e32 v250, v250, v90
	v_add_f32_e32 v251, v251, v91
	v_cvt_pk_bf16_f32 v221, v90, v91
	v_exp_f32_e32 v94, v94
	v_exp_f32_e32 v95, v95
	v_add_f32_e32 v248, v248, v92
	v_add_f32_e32 v249, v249, v93
	v_cvt_pk_bf16_f32 v222, v92, v93
	v_exp_f32_e32 v64, v64
	v_exp_f32_e32 v65, v65
	v_add_f32_e32 v250, v250, v94
	v_add_f32_e32 v251, v251, v95
	v_cvt_pk_bf16_f32 v223, v94, v95
	v_exp_f32_e32 v66, v66
	v_exp_f32_e32 v67, v67
	v_add_f32_e32 v248, v248, v64
	v_add_f32_e32 v249, v249, v65
	v_cvt_pk_bf16_f32 v224, v64, v65
	v_exp_f32_e32 v68, v68
	v_exp_f32_e32 v69, v69
	v_add_f32_e32 v250, v250, v66
	v_add_f32_e32 v251, v251, v67
	v_cvt_pk_bf16_f32 v225, v66, v67
	v_exp_f32_e32 v70, v70
	v_exp_f32_e32 v71, v71
	v_add_f32_e32 v248, v248, v68
	v_add_f32_e32 v249, v249, v69
	v_cvt_pk_bf16_f32 v226, v68, v69
	v_exp_f32_e32 v72, v72
	v_exp_f32_e32 v73, v73
	v_add_f32_e32 v250, v250, v70
	v_add_f32_e32 v251, v251, v71
	v_cvt_pk_bf16_f32 v227, v70, v71
	v_exp_f32_e32 v74, v74
	v_exp_f32_e32 v75, v75
	v_add_f32_e32 v248, v248, v72
	v_add_f32_e32 v249, v249, v73
	v_cvt_pk_bf16_f32 v228, v72, v73
	v_exp_f32_e32 v76, v76
	v_exp_f32_e32 v77, v77
	v_add_f32_e32 v250, v250, v74
	v_add_f32_e32 v251, v251, v75
	v_cvt_pk_bf16_f32 v229, v74, v75
	v_exp_f32_e32 v78, v78
	v_exp_f32_e32 v79, v79
	v_add_f32_e32 v248, v248, v76
	v_add_f32_e32 v249, v249, v77
	v_cvt_pk_bf16_f32 v230, v76, v77
	v_add_f32_e32 v250, v250, v78
	v_add_f32_e32 v251, v251, v79
	v_cvt_pk_bf16_f32 v231, v78, v79
	v_add_f32_e32 v248, v248, v249
	v_add_f32_e32 v250, v250, v251
	v_add_f32_e32 v248, v248, v250
	v_add_f32_e32 v170, v170, v248
	s_waitcnt lgkmcnt(0)
	s_barrier
	s_cmp_lg_u64 s[86:87], 0
	s_cbranch_scc0 .Lmla_noq18
	s_mul_i32 s18, s71, 0x60
	s_ashr_i32 s19, s18, 31
	v_lshl_add_u64 v[192:193], s[18:19], 1, v[164:165]
	global_load_dwordx4 v[128:131], v[192:193], off offset:192
	global_load_dwordx4 v[124:127], v[192:193], off offset:224
	global_load_dwordx4 v[120:123], v[192:193], off offset:256
	global_load_dwordx4 v[116:119], v[192:193], off offset:288
	global_load_dwordx4 v[112:115], v[192:193], off offset:320
	global_load_dwordx4 v[108:111], v[192:193], off offset:352
	s_waitcnt vmcnt(0)

; #define ATT_BAR() do { __builtin_amdgcn_sched_barrier(0); asm volatile("s_waitcnt lgkmcnt(0)\n\ts_barrier" ::: "memory"); __builtin_amdgcn_sched_barrier(0); } while (0)
; template <int GRP> ...
;     ...
;     S.o0 = (f32x16){}; S.o1 = (f32x16){}; S.mhat = 0.f; S.lrun = 0.f; S.ssq = 0.f; S.refnz = 0;
; #pragma unroll
;     for (int i = 0; i < 16; ++i) S.pw[i] = 0u;
;     { u32x4 kB, pB = {0u, 0u, 0u, 0u};
;       att_ldk<GRP>(C, 0, kA, pA); att_ldk<GRP>(C, 1, kB, pB); att_ldv<GRP>(C, 0, vA);
;       att_stk<GRP>(C, 0, kA, pA); att_stk<GRP>(C, 1, kB, pB); att_stv<GRP>(C, 0, vA); }
;     att_ldk<GRP>(C, 2, kA, pA); att_ldv<GRP>(C, 1, vA);
; #pragma unroll
;     for (int ks = 0; ks < NKS; ++ks) S.qr[ks] = *(const bf16x8*)(Q + C.qrow * QP + C.h0 * DK + ks * 16 + hi * 8);
;     ATT_BAR();
;     f32x16 pa0 = {}, pa1 = {}, pb0 = {}, pb1 = {};
;     {
;         bf16x8 kf[2 * NKS]; att_kfrag<GRP, 0, NKS>(C, 0, kf);
; #pragma unroll
;         for (int ks = 0; ks < NKS; ++ks) { pa0 = __builtin_amdgcn_mfma_f32_32x32x16_bf16(kf[2 * ks], S.qr[ks], pa0, 0, 0, 0); pa1 = __builtin_amdgcn_mfma_f32_32x32x16_bf16(kf[2 * ks + 1], S.qr[ks], pa1, 0, 0, 0); }
;     }
;     if (wid >= 4) __builtin_amdgcn_s_setprio(1);
;     asm volatile("s_nop 15\n\ts_nop 7" : "+v"(pa0), "+v"(pa1));
;     for (int s = 0; s < NSTEP - 2; s += 2) { att_step<GRP, true>(C, S, s, pa0, pa1, pb0, pb1, kA, pA, vA); att_step<GRP, true>(C, S, s + 1, pb0, pb1, pa0, pa1, kA, pA, vA); }
.LBB0_807:
	v_lshlrev_b32_e32 v8, 3, v3
	v_mad_u32_u24 v10, v6, s37, v96
	v_lshlrev_b64 v[6:7], 11, v[132:133]
	v_mov_b32_e32 v9, v97
	v_mad_u64_u32 v[0:1], s[6:7], v0, s37, v[2:3]
	v_lshl_add_u64 v[134:135], s[48:49], 0, v[6:7]
	v_lshlrev_b32_e32 v96, 1, v8
	v_mov_b32_e32 v152, 0
	s_mov_b32 s62, 0
	v_cmp_eq_u32_e64 s[0:1], 0, v3
	v_lshlrev_b32_e32 v136, 2, v3
	v_lshl_add_u64 v[142:143], v[134:135], 0, v[8:9]
	v_lshl_add_u64 v[144:145], v[4:5], 0, v[96:97]
	v_add_u32_e32 v146, 0, v10
	v_add_u32_e32 v147, 0, v0
	v_mov_b32_e32 v137, 0
	s_mov_b32 s61, 0
	v_mov_b32_e32 v148, 0
	v_mov_b32_e32 v0, 0
	v_mov_b32_e32 v1, v152
	v_mov_b32_e32 v2, v152
	v_mov_b32_e32 v3, v152
	v_mov_b32_e32 v4, v152
	v_mov_b32_e32 v5, v152
	v_mov_b32_e32 v6, v152
	v_mov_b32_e32 v7, v152
	v_mov_b32_e32 v8, v152
	v_mov_b32_e32 v9, v152
	v_mov_b32_e32 v10, v152
	v_mov_b32_e32 v11, v152
	v_mov_b32_e32 v12, v152
	v_mov_b32_e32 v13, v152
	v_mov_b32_e32 v14, v152
	v_mov_b32_e32 v15, v152
	v_mov_b32_e32 v16, 0
	v_mov_b32_e32 v17, v152
	v_mov_b32_e32 v18, v152
	v_mov_b32_e32 v19, v152
	v_mov_b32_e32 v20, v152
	v_mov_b32_e32 v21, v152
	v_mov_b32_e32 v22, v152
	v_mov_b32_e32 v23, v152
	v_mov_b32_e32 v24, v152
	v_mov_b32_e32 v25, v152
	v_mov_b32_e32 v26, v152
	v_mov_b32_e32 v27, v152
	v_mov_b32_e32 v28, v152
	v_mov_b32_e32 v29, v152
	v_mov_b32_e32 v30, v152
	v_mov_b32_e32 v31, v152
	s_nop 15
	s_nop 7
	s_branch .Lpagefit_4
	s_nop 0
	s_nop 0
	s_nop 0
	s_nop 0
	s_nop 0
	s_nop 0
	s_nop 0
	s_nop 0
	s_nop 0
	s_nop 0
	s_nop 0
	s_nop 0
	s_nop 0
	s_nop 0
	s_nop 0
	s_nop 0
	s_nop 0
	s_nop 0
	s_nop 0
	s_nop 0
	s_nop 0
	s_nop 0
	s_nop 0
	s_nop 0
	s_nop 0
	s_nop 0
	s_nop 0
	s_nop 0
	s_nop 0
	s_nop 0
	s_nop 0
	s_nop 0
	s_nop 0
	s_nop 0
	s_nop 0
	s_nop 0
	s_nop 0
	s_nop 0
	s_nop 0
	s_nop 0
	s_nop 0
	s_nop 0
	s_nop 0
	s_nop 0
	s_nop 0
	s_nop 0
	s_nop 0
	s_nop 0
	s_nop 0
	s_nop 0
	s_nop 0
	s_nop 0
	s_nop 0
	s_nop 0
	s_nop 0
	s_nop 0
	s_nop 0
	s_nop 0
	s_nop 0
	s_nop 0
	s_nop 0
	s_nop 0
	s_nop 0
	s_nop 0
	s_nop 0
	s_nop 0
	s_nop 0
	s_nop 0
	s_nop 0
	s_nop 0
	s_nop 0
	s_nop 0
	s_nop 0
	s_nop 0
	s_nop 0
	s_nop 0
	s_nop 0
	s_nop 0
	s_nop 0
	s_nop 0
	s_nop 0
	s_nop 0
	s_nop 0
	s_nop 0
	s_nop 0
	s_nop 0
	s_nop 0
	s_nop 0
	s_nop 0
	s_nop 0
	s_nop 0
	s_nop 0
	s_nop 0
	s_nop 0
	s_nop 0
	s_nop 0
	s_nop 0
	s_nop 0
	s_nop 0
	s_nop 0
	s_nop 0
	s_nop 0
	s_nop 0
	s_nop 0
	s_nop 0
	s_nop 0
	s_nop 0
	s_nop 0
	s_nop 0
	s_nop 0
	s_nop 0
	s_nop 0
	s_nop 0
	s_nop 0
	s_nop 0
	s_nop 0
	s_nop 0
	s_nop 0
	s_nop 0
	s_nop 0
	s_nop 0
	s_nop 0
	s_nop 0
	s_nop 0
	s_nop 0
	s_nop 0
	s_nop 0
	s_nop 0
	s_nop 0
	s_nop 0
	s_nop 0
	s_nop 0
	s_nop 0
	s_nop 0
	s_nop 0
	s_nop 0
	s_nop 0
	s_nop 0
	s_nop 0
	s_nop 0
	s_nop 0
	s_nop 0
	s_nop 0
	s_nop 0
	s_nop 0
	s_nop 0
	s_nop 0
	s_nop 0
	s_nop 0
	s_nop 0
	s_nop 0
	s_nop 0
	s_nop 0
	s_nop 0
	s_nop 0
	s_nop 0
	s_nop 0
	s_nop 0
	s_nop 0
	s_nop 0
	s_nop 0
	s_nop 0
	s_nop 0
	s_nop 0
	s_nop 0
	s_nop 0
	s_nop 0
	s_nop 0
	s_nop 0
	s_nop 0
	s_nop 0
	s_nop 0
	s_nop 0
	s_nop 0
	s_nop 0
	s_nop 0
	s_nop 0
	s_nop 0
	s_nop 0
	s_nop 0
	s_nop 0
	s_nop 0
	s_nop 0
	s_nop 0
	s_nop 0
	s_nop 0
	s_nop 0
	s_nop 0
	s_nop 0
	s_nop 0
	s_nop 0
	s_nop 0
	s_nop 0
	s_nop 0
	s_nop 0
	s_nop 0
	s_nop 0
	s_nop 0
	s_nop 0
	s_nop 0
	s_nop 0
	s_nop 0
	s_nop 0
	s_nop 0
	s_nop 0
	s_nop 0
	s_nop 0
	s_nop 0
	s_nop 0
	s_nop 0
	s_nop 0
	s_nop 0
	s_nop 0
	s_nop 0
	s_nop 0
	s_nop 0
	s_nop 0
	s_nop 0
	s_nop 0
	s_nop 0
	s_nop 0
	s_nop 0
	s_nop 0
	s_nop 0
	s_nop 0
	s_nop 0
	s_nop 0
	s_nop 0
	s_nop 0
	s_nop 0
	s_nop 0
	s_nop 0
	s_nop 0
	s_nop 0
	s_nop 0
	s_nop 0
	s_nop 0
	s_nop 0
	s_nop 0
	s_nop 0
	s_nop 0
	s_nop 0
	s_nop 0
	s_nop 0
	s_nop 0
	s_nop 0
	s_nop 0
	s_nop 0
	s_nop 0
	s_nop 0
	s_nop 0
	s_nop 0
	s_nop 0
	s_nop 0
	s_nop 0
	s_nop 0
	s_nop 0
	s_nop 0
	s_nop 0
	s_nop 0
	s_nop 0
	s_nop 0
	s_nop 0
	s_nop 0
	s_nop 0
	s_nop 0
	s_nop 0
	s_nop 0
	s_nop 0
	s_nop 0
	s_nop 0
	s_nop 0
	s_nop 0
	s_nop 0
	s_nop 0
	s_nop 0
	s_nop 0
	s_nop 0
	s_nop 0
	s_nop 0
	s_nop 0
	s_nop 0
	s_nop 0
	s_nop 0
	s_nop 0
	s_nop 0
	s_nop 0
	s_nop 0
	s_nop 0
	s_nop 0
	s_nop 0
	s_nop 0
	s_nop 0
	s_nop 0
	s_nop 0
	s_nop 0
	s_nop 0
	s_nop 0
	s_nop 0
	s_nop 0
	s_nop 0
	s_nop 0
	s_nop 0
	s_nop 0
	s_nop 0
	s_nop 0
	s_nop 0
	s_nop 0
	s_nop 0
	s_nop 0
	s_nop 0
	s_nop 0
	s_nop 0
	s_nop 0
	s_nop 0
	s_nop 0
	s_nop 0
	s_nop 0
	s_nop 0
	s_nop 0
	s_nop 0
	s_nop 0
	s_nop 0
	s_nop 0
	s_nop 0
	s_nop 0
	s_nop 0
	s_nop 0
	s_nop 0
	s_nop 0
	s_nop 0
	s_nop 0
	s_nop 0
	s_nop 0
	s_nop 0
	s_nop 0
	s_nop 0
	s_nop 0
	s_nop 0
	s_nop 0
	s_nop 0
	s_nop 0
	s_nop 0
	s_nop 0
	s_nop 0
	s_nop 0
	s_nop 0
	s_nop 0
	s_nop 0
	s_nop 0
	s_nop 0
	s_nop 0
	s_nop 0
	s_nop 0
	s_nop 0
	s_nop 0
	s_nop 0
	s_nop 0
	s_nop 0
	s_nop 0
	s_nop 0
	s_nop 0
	s_nop 0
	s_nop 0
	s_nop 0
	s_nop 0
	s_nop 0
	s_nop 0
	s_nop 0
	s_nop 0
	s_nop 0
	s_nop 0
	s_nop 0
	s_nop 0
	s_nop 0
	s_nop 0
	s_nop 0
	s_nop 0
	s_nop 0
	s_nop 0
	s_nop 0
	s_nop 0
	s_nop 0
	s_nop 0
	s_nop 0
	s_nop 0
	s_nop 0
	s_nop 0
	s_nop 0
	s_nop 0
	s_nop 0
	s_nop 0
	s_nop 0
	s_nop 0
	s_nop 0
	s_nop 0
	s_nop 0
	s_nop 0
	s_nop 0
	s_nop 0
	s_nop 0
	s_nop 0
	s_nop 0
	s_nop 0
	s_nop 0
	s_nop 0
	s_nop 0
	s_nop 0
	s_nop 0
	s_nop 0
	s_nop 0
